# P0: fifth-round transpose items moved to workgroups without an adaLN GEMV item (critical-path rebalance)
# baseline (speedup 1.0000x reference)
; __device__ __forceinline__ void p0_prologue(const Args& A, char* lds, int vcu, int G) {
;     ...
;     for (int it = gw; it < NITEMS; it += NGW) {
;         int r = it;
;         if (r < I0) { transpose_item<0>(A.in[I_EINW], 1024, 6672, NP0, (bf16*)(ws + WS_WT0), scr, r, lane); continue; } r -= I0;
;         if (r < I1) { transpose_item<1>(A.in[I_OINW], 1024, 7192, NP1, (bf16*)(ws + WS_WT1), scr, r, lane); continue; } r -= I1;
;         if (r < IO) { transpose_item<2>(A.in[I_EOUTW], 2048, 1024, 1024, (bf16*)(ws + WS_WO0), scr, r, lane, G == 256 ? A.in[I_ENORMG] : nullptr); continue; } r -= IO;
;         if (r < IO) { transpose_item<2>(A.in[I_OOUTW], 2048, 1024, 1024, (bf16*)(ws + WS_WO1), scr, r, lane); continue; } r -= IO;
;         transpose_item<2>(A.in[I_OGLUW], 512, 512, 512, (bf16*)(ws + WS_WG), scr, r, lane);
;     }
.LBB0_33:
	s_or_b64 exec, exec, s[52:53]
	v_add_u32_e32 v18, s44, v18
	v_lshrrev_b32_e32 v180, 11, v18
	v_subrev_u32_e32 v181, 0x2000, v18
	v_lshrrev_b32_e32 v182, 3, v181
	v_and_b32_e32 v183, 31, v182
	v_lshrrev_b32_e32 v182, 5, v182
	v_and_b32_e32 v181, 7, v181
	v_lshl_add_u32 v181, v182, 3, v181
	v_subrev_u32_e32 v182, 12, v183
	v_lshl_add_u32 v181, v182, 6, v181
	v_add_u32_e32 v181, 0x2000, v181
	v_cmp_gt_u32_e32 vcc, 12, v183
	v_mov_b32_e32 v182, 0x10000
	s_nop 1
	v_cndmask_b32_e32 v181, v181, v182, vcc
	v_cmp_eq_u32_e32 vcc, 4, v180
	s_nop 1
	v_cndmask_b32_e32 v18, v18, v181, vcc
	v_cmp_lt_i32_e32 vcc, s94, v18
	s_or_b64 s[50:51], vcc, s[50:51]
	v_lshlrev_b32_e32 v27, 5, v18
	s_andn2_b64 exec, exec, s[50:51]
	s_cbranch_execz .LBB0_287
